# HM head-norm streaming moved out of the attention items into the idle time of the preceding (now split) grid barrier
# speedup vs baseline: 1.0013x; 1.0013x over previous
; __device__ __forceinline__ unsigned xb_ld(unsigned* p)              { return __hip_atomic_load(p, __ATOMIC_RELAXED, __HIP_MEMORY_SCOPE_AGENT); }
; __device__ __forceinline__ void xcd_barrier_complete(unsigned* bar, unsigned x, unsigned& nloc, unsigned& nx) {
;     const unsigned G = gridDim.x * gridDim.y * gridDim.z;
;     unsigned sum, cnt, mine, sp = 0u;
;     for (;;) {
;         sum = 0u; cnt = 0u; mine = 0u;
; #pragma unroll
;         for (unsigned j = 0; j < 16; ++j) { const unsigned c = xb_ld(&bar[XB_XCNT(j)]); sum += c; cnt += (c > 0u) ? 1u : 0u; mine = (j == x) ? c : mine; }
; __device__ __forceinline__ void xcd_barrier(const XcdBarrier& b) {
;     asm volatile("s_waitcnt vmcnt(0)" ::: "memory");
;     __syncthreads();
;     if (threadIdx.x == 0) {
;         unsigned* bar = b.bar;
;         __builtin_amdgcn_s_waitcnt(0);
;         unsigned nloc = b.st[0], nx = b.st[1];
;         if (nloc == 0u) { xcd_barrier_complete(bar, b.x, nloc, nx); b.st[0] = nloc; b.st[1] = nx; }
.LBB0_520:
	s_mov_b32 s101, 0
	s_cmp_gt_i32 s91, 5
	s_cselect_b64 s[2:3], -1, 0
	s_and_b64 s[0:1], s[0:1], s[2:3]
	s_andn2_b64 vcc, exec, s[0:1]
	s_cbranch_vccnz .LBB0_570
	s_cmp_eq_u32 s82, 0x100
	s_cselect_b32 s101, 1, 0
	s_waitcnt vmcnt(0)
	s_waitcnt vmcnt(0) lgkmcnt(0)
	s_barrier
	s_mov_b64 s[0:1], exec
	v_readlane_b32 s4, v254, 1
	v_readlane_b32 s5, v254, 2
	s_and_b64 s[4:5], s[0:1], s[4:5]
	s_mov_b64 exec, s[4:5]
	s_cbranch_execz .LBB0_569
	v_readlane_b32 s4, v254, 22
	s_waitcnt vmcnt(0) expcnt(0) lgkmcnt(0)
	s_nop 0
	v_mov_b32_e32 v0, s4
	ds_read_b32 v2, v0
	ds_read_b32 v0, v0 offset:4
	s_waitcnt lgkmcnt(1)
	v_cmp_ne_u32_e32 vcc, 0, v2
	s_cbranch_vccnz .LBB0_537
	v_readlane_b32 s4, v254, 0
	s_mul_i32 s33, s83, s4
	s_add_u32 s4, s88, 0xffc0200
	s_addc_u32 s5, s89, 0
	s_add_u32 s6, s88, 0xffc0400
	s_addc_u32 s7, s89, 0
	s_add_u32 s8, s88, 0xffc0500
	s_addc_u32 s9, s89, 0
	s_add_u32 s10, s88, 0xffc0600
	s_addc_u32 s11, s89, 0
	s_add_u32 s12, s88, 0xffc0700
	s_addc_u32 s13, s89, 0
	s_add_u32 s14, s88, 0xffc0800
	s_addc_u32 s15, s89, 0
	s_add_u32 s16, s88, 0xffc0900
	s_addc_u32 s17, s89, 0
	s_add_u32 s18, s88, 0xffc0a00
	s_addc_u32 s19, s89, 0
	s_add_u32 s20, s88, 0xffc0b00
	s_addc_u32 s21, s89, 0
	s_add_u32 s22, s88, 0xffc0c00
	s_addc_u32 s23, s89, 0
	s_add_u32 s24, s88, 0xffc0d00
	s_addc_u32 s25, s89, 0
	s_add_u32 s26, s88, 0xffc0e00
	s_addc_u32 s27, s89, 0
	s_add_u32 s28, s88, 0xffc0f00
	s_addc_u32 s29, s89, 0
	s_add_u32 s30, s88, 0xffc1000
	s_addc_u32 s31, s89, 0
	s_add_u32 s34, s88, 0xffc1100
	s_addc_u32 s35, s89, 0
	s_add_u32 s36, s88, 0xffc1200
	s_addc_u32 s37, s89, 0
	s_add_u32 s38, s88, 0xffc1300
	s_mul_i32 s33, s33, s82
	s_addc_u32 s39, s89, 0
	s_mov_b32 s46, 1
	v_mov_b32_e32 v16, 0
	s_branch .LBB0_525

; __device__ __forceinline__ unsigned xb_ld(unsigned* p)              { return __hip_atomic_load(p, __ATOMIC_RELAXED, __HIP_MEMORY_SCOPE_AGENT); }
; __device__ __forceinline__ unsigned xb_add(unsigned* p, unsigned v) { return __hip_atomic_fetch_add(p, v, __ATOMIC_RELAXED, __HIP_MEMORY_SCOPE_AGENT); }
; #define XB_SPIN(cond, bar) do { unsigned _sp = 0; while (cond) { __builtin_amdgcn_s_sleep(1); \
;     if ((++_sp & 255u) == 0u) { if (xb_ld(&(bar)[XB_TMO])) break; if (_sp > XB_SPIN_CAP) { atomicAdd(&(bar)[XB_TMO], 1u); break; } } } } while (0)
; __device__ __forceinline__ void xcd_barrier_complete(unsigned* bar, unsigned x, unsigned& nloc, unsigned& nx) {
;     ...
;         for (unsigned j = 0; j < 16; ++j) { const unsigned c = xb_ld(&bar[XB_XCNT(j)]); sum += c; cnt += (c > 0u) ? 1u : 0u; mine = (j == x) ? c : mine; }
;         if (sum == G) break;
;         __builtin_amdgcn_s_sleep(1);
;         if ((++sp & 255u) == 0u) { if (xb_ld(&bar[XB_TMO])) break; if (sp > XB_SPIN_CAP) { atomicAdd(&bar[XB_TMO], 1u); break; } }
;     }
;     nloc = mine > 0u ? mine : 1u; nx = cnt > 0u ? cnt : 1u;
; }
; __device__ __forceinline__ void xcd_barrier(const XcdBarrier& b) {
;     asm volatile("s_waitcnt vmcnt(0)" ::: "memory");
;     __syncthreads();
;     if (threadIdx.x == 0) {
;         unsigned* bar = b.bar;
;         __builtin_amdgcn_s_waitcnt(0);
;         unsigned nloc = b.st[0], nx = b.st[1];
;         if (nloc == 0u) { xcd_barrier_complete(bar, b.x, nloc, nx); b.st[0] = nloc; b.st[1] = nx; }
;         const unsigned old = xb_add(&bar[XB_XSUB(b.x)], 1u);
;         const unsigned gen = old / nloc;
;         if (old + 1u == (gen + 1u) * nloc) {
;             __builtin_amdgcn_fence(__ATOMIC_RELEASE, "agent");
;             asm volatile("s_waitcnt vmcnt(0)" ::: "memory");
;             const unsigned og = xb_add(&bar[XB_TOP], 1u);
;             const unsigned tg = og / nx;
;             if (og + 1u == (tg + 1u) * nx) xb_add(&bar[XB_TOPGEN], 1u);
;             else XB_SPIN(xb_ld(&bar[XB_TOPGEN]) == tg, bar);
;             __builtin_amdgcn_fence(__ATOMIC_ACQUIRE, "agent");
;             xb_add(&bar[XB_XGEN(b.x)], 1u);
;             asm volatile("s_waitcnt vmcnt(0)" ::: "memory");
;         } else {
;             XB_SPIN(xb_ld(&bar[XB_XGEN(b.x)]) == gen, bar);
.LBB0_536:
	v_readlane_b32 s4, v254, 3
	s_cmp_eq_u32 s4, 0
	s_cselect_b64 vcc, -1, 0
	s_cmp_eq_u32 s4, 1
	v_cndmask_b32_e32 v16, 0, v15, vcc
	s_cselect_b64 vcc, -1, 0
	s_cmp_eq_u32 s4, 2
	v_cndmask_b32_e32 v16, v16, v0, vcc
	s_cselect_b64 vcc, -1, 0
	s_cmp_eq_u32 s4, 3
	v_cndmask_b32_e32 v16, v16, v1, vcc
	s_cselect_b64 vcc, -1, 0
	s_cmp_eq_u32 s4, 4
	v_cndmask_b32_e32 v16, v16, v2, vcc
	s_cselect_b64 vcc, -1, 0
	s_cmp_eq_u32 s4, 5
	v_cndmask_b32_e32 v16, v16, v3, vcc
	s_cselect_b64 vcc, -1, 0
	s_cmp_eq_u32 s4, 6
	v_cndmask_b32_e32 v16, v16, v4, vcc
	s_cselect_b64 vcc, -1, 0
	s_cmp_eq_u32 s4, 7
	v_cndmask_b32_e32 v16, v16, v5, vcc
	s_cselect_b64 vcc, -1, 0
	s_cmp_eq_u32 s4, 8
	v_cndmask_b32_e32 v16, v16, v6, vcc
	s_cselect_b64 vcc, -1, 0
	s_cmp_eq_u32 s4, 9
	v_cndmask_b32_e32 v16, v16, v7, vcc
	s_cselect_b64 vcc, -1, 0
	s_cmp_eq_u32 s4, 10
	v_cndmask_b32_e32 v16, v16, v8, vcc
	s_cselect_b64 vcc, -1, 0
	s_cmp_eq_u32 s4, 11
	v_cndmask_b32_e32 v16, v16, v9, vcc
	s_cselect_b64 vcc, -1, 0
	s_cmp_eq_u32 s4, 12
	v_cndmask_b32_e32 v16, v16, v10, vcc
	s_cselect_b64 vcc, -1, 0
	s_cmp_eq_u32 s4, 13
	v_cndmask_b32_e32 v16, v16, v11, vcc
	s_cselect_b64 vcc, -1, 0
	s_cmp_eq_u32 s4, 14
	v_cndmask_b32_e32 v16, v16, v12, vcc
	s_cselect_b64 vcc, -1, 0
	s_cmp_eq_u32 s4, 15
	v_cndmask_b32_e32 v16, v16, v13, vcc
	s_cselect_b64 vcc, -1, 0
	v_cndmask_b32_e32 v16, v16, v14, vcc
	v_cmp_ne_u32_e32 vcc, 0, v15
	v_readlane_b32 s4, v254, 22
	s_nop 0
	v_cndmask_b32_e64 v15, 0, 1, vcc
	v_cmp_ne_u32_e32 vcc, 0, v0
	s_nop 1
	v_addc_co_u32_e32 v0, vcc, 0, v15, vcc
	v_cmp_ne_u32_e32 vcc, 0, v1
	s_nop 1
	v_cndmask_b32_e64 v1, 0, 1, vcc
	v_cmp_ne_u32_e32 vcc, 0, v2
	v_max_u32_e32 v2, 1, v16
	s_nop 0
	v_addc_co_u32_e32 v0, vcc, v0, v1, vcc
	v_cmp_ne_u32_e32 vcc, 0, v3
	s_nop 1
	v_cndmask_b32_e64 v1, 0, 1, vcc
	v_cmp_ne_u32_e32 vcc, 0, v4
	s_nop 1
	v_addc_co_u32_e32 v0, vcc, v0, v1, vcc
	v_cmp_ne_u32_e32 vcc, 0, v5
	s_nop 1
	v_cndmask_b32_e64 v1, 0, 1, vcc
	v_cmp_ne_u32_e32 vcc, 0, v6
	s_nop 1
	v_addc_co_u32_e32 v0, vcc, v0, v1, vcc
	v_cmp_ne_u32_e32 vcc, 0, v7
	s_nop 1
	v_cndmask_b32_e64 v1, 0, 1, vcc
	v_cmp_ne_u32_e32 vcc, 0, v8
	s_nop 1
	v_addc_co_u32_e32 v0, vcc, v0, v1, vcc
	v_cmp_ne_u32_e32 vcc, 0, v9
	s_nop 1
	v_cndmask_b32_e64 v1, 0, 1, vcc
	v_cmp_ne_u32_e32 vcc, 0, v10
	s_nop 1
	v_addc_co_u32_e32 v0, vcc, v0, v1, vcc
	v_cmp_ne_u32_e32 vcc, 0, v11
	s_nop 1
	v_cndmask_b32_e64 v1, 0, 1, vcc
	v_cmp_ne_u32_e32 vcc, 0, v12
	s_nop 1
	v_addc_co_u32_e32 v0, vcc, v0, v1, vcc
	v_cmp_ne_u32_e32 vcc, 0, v13
	s_nop 1
	v_cndmask_b32_e64 v1, 0, 1, vcc
	v_cmp_ne_u32_e32 vcc, 0, v14
	s_nop 1
	v_addc_co_u32_e32 v0, vcc, v0, v1, vcc
	v_max_u32_e32 v0, 1, v0
	v_mov_b32_e32 v1, s4
	ds_write_b32 v1, v2
	ds_write_b32 v1, v0 offset:4
.LBB0_537:
	v_readlane_b32 s4, v254, 3
	s_lshl_b32 s4, s4, 8
	s_add_u32 s4, s92, s4
	s_addc_u32 s5, s93, 0
	v_mov_b32_e32 v1, 0x1000
	v_mov_b32_e32 v3, 1
	global_atomic_add v3, v1, v3, s[4:5] offset:1024 sc0
	v_cvt_f32_u32_e32 v1, v2
	v_sub_u32_e32 v4, 0, v2
	v_rcp_iflag_f32_e32 v1, v1
	s_nop 0
	v_mul_f32_e32 v1, 0x4f7ffffe, v1
	v_cvt_u32_f32_e32 v1, v1
	v_mul_lo_u32 v4, v4, v1
	v_mul_hi_u32 v4, v1, v4
	v_add_u32_e32 v1, v1, v4
	s_waitcnt vmcnt(0)
	v_mul_hi_u32 v1, v3, v1
	v_mul_lo_u32 v4, v1, v2
	v_sub_u32_e32 v4, v3, v4
	v_add_u32_e32 v5, 1, v1
	v_cmp_ge_u32_e32 vcc, v4, v2
	v_add_u32_e32 v3, 1, v3
	s_nop 0
	v_cndmask_b32_e32 v1, v1, v5, vcc
	v_sub_u32_e32 v5, v4, v2
	v_cndmask_b32_e32 v4, v4, v5, vcc
	v_add_u32_e32 v5, 1, v1
	v_cmp_ge_u32_e32 vcc, v4, v2
	s_nop 1
	v_cndmask_b32_e32 v1, v1, v5, vcc
	v_mul_lo_u32 v4, v2, v1
	v_add_u32_e32 v2, v4, v2
	v_cmp_ne_u32_e32 vcc, v3, v2
	s_and_saveexec_b64 s[6:7], vcc
	s_xor_b64 s[6:7], exec, s[6:7]
	s_cbranch_execz .LBB0_551
	s_cmp_eq_u32 s101, 1
	s_cbranch_scc1 .Lsk4_nl
	s_waitcnt lgkmcnt(0)
	v_mov_b32_e32 v0, 0x2000
	global_load_dword v0, v0, s[4:5] offset:1024 sc1
	s_add_u32 s12, s4, 0x2400
	s_addc_u32 s13, s5, 0
	s_waitcnt vmcnt(0)
	v_cmp_eq_u32_e32 vcc, v0, v1
	s_and_saveexec_b64 s[8:9], vcc
	s_cbranch_execz .LBB0_550
	s_add_u32 s10, s88, 0xffc0200
	s_addc_u32 s11, s89, 0
	s_mov_b32 s24, 1
	s_mov_b64 s[14:15], 0
	v_mov_b32_e32 v0, 0
	s_branch .LBB0_541

; __device__ __forceinline__ void st_wt16(void* p, u32x4 v) { asm volatile("global_store_dwordx4 %0, %1, off sc1\n\ts_nop 1" : : "v"(p), "v"(v) : "memory"); }
; __device__ __forceinline__ void p5_fixup(const Params& p) {
;     ...
;     for (int v0 = gtid; v0 < T_TOK * 128; v0 += 4 * gsz) {
;         u32x4 hv[4]; float4 s0[4], s1[4];
; #pragma unroll
;         for (int u = 0; u < 4; ++u) { const int v = v0 + u * gsz; if (v < T_TOK * 128) { const int row = v >> 7, head = (v >> 5) & 3;
;             hv[u] = __builtin_nontemporal_load((const u32x4*)(HM + (size_t)v * 8)); s0[u] = *(const float4*)(SSQ + ((size_t)row * 4 + head) * 8); s1[u] = *(const float4*)(SSQ + ((size_t)row * 4 + head) * 8 + 4); } }
; #pragma unroll
;         for (int u = 0; u < 4; ++u) { const int v = v0 + u * gsz; if (v < T_TOK * 128) {
;             const float ss = (s0[u].x + s0[u].y) + (s0[u].z + s0[u].w) + (s1[u].x + s1[u].y) + (s1[u].z + s1[u].w);
;             const float rstd = rsqrtf(ss * (1.0f / 256.0f) + EPS);
;             float f[8]; unpack8(hv[u], f);
; #pragma unroll
;             for (int e = 0; e < 8; ++e) f[e] *= rstd;
;             st_wt16(HM + (size_t)v * 8, pack8(f)); } }
;     }
.Lattn_perm_done:
	s_mov_b32 s99, 0
	s_cmp_lt_i32 s90, 6
	s_cselect_b64 s[0:1], -1, 0
	s_and_b64 s[96:97], s[0:1], s[2:3]
	s_andn2_b64 vcc, exec, s[96:97]
	s_cbranch_vccnz .LBB0_629
	s_cmp_eq_u32 s82, 0x100
	s_cbranch_scc0 .Lf4_done
	v_readlane_b32 s96, v254, 23
	v_readlane_b32 s97, v254, 24
	v_lshlrev_b32_e32 v64, 4, v212
	v_mov_b32_e32 v65, s84
	v_lshl_add_u32 v64, v65, 15, v64
	v_lshlrev_b32_e32 v65, 11, v65
	v_and_b32_e32 v60, 0x1e0, v212
	v_add_u32_e32 v65, v65, v60
	v_and_b32_e32 v60, 7, v212
	v_lshl_add_u32 v65, v60, 2, v65
	v_add_u32_e32 v65, 0xfd80000, v65
	s_nop 4
	v_mov_b32_e32 v62, v64
	global_load_dwordx4 v[20:23], v62, s[96:97] nt
	v_add_u32_e32 v62, 0x2000, v64
	global_load_dwordx4 v[24:27], v62, s[96:97] nt
	v_add_u32_e32 v62, 0x4000, v64
	global_load_dwordx4 v[28:31], v62, s[96:97] nt
	v_add_u32_e32 v62, 0x6000, v64
	global_load_dwordx4 v[32:35], v62, s[96:97] nt
	v_add_u32_e32 v62, 0x800000, v64
	global_load_dwordx4 v[36:39], v62, s[96:97] nt
	v_add_u32_e32 v62, 0x802000, v64
	global_load_dwordx4 v[40:43], v62, s[96:97] nt
	v_add_u32_e32 v62, 0x804000, v64
	global_load_dwordx4 v[44:47], v62, s[96:97] nt
	v_add_u32_e32 v62, 0x806000, v64
	global_load_dwordx4 v[48:51], v62, s[96:97] nt
	v_mov_b32_e32 v62, v65
	global_load_dword v52, v62, s[88:89]
	v_add_u32_e32 v62, 0x200, v65
	global_load_dword v53, v62, s[88:89]
	v_add_u32_e32 v62, 0x400, v65
	global_load_dword v54, v62, s[88:89]
	v_add_u32_e32 v62, 0x600, v65
	global_load_dword v55, v62, s[88:89]
	v_add_u32_e32 v62, 0x80000, v65
	global_load_dword v56, v62, s[88:89]
	v_add_u32_e32 v62, 0x80200, v65
	global_load_dword v57, v62, s[88:89]
	v_add_u32_e32 v62, 0x80400, v65
	global_load_dword v58, v62, s[88:89]
	v_add_u32_e32 v62, 0x80600, v65
	global_load_dword v59, v62, s[88:89]
	s_waitcnt vmcnt(0)
	v_add_f32_dpp v52, v52, v52 quad_perm:[1,0,3,2] row_mask:0xf bank_mask:0xf
	v_add_f32_dpp v53, v53, v53 quad_perm:[1,0,3,2] row_mask:0xf bank_mask:0xf
	v_add_f32_dpp v54, v54, v54 quad_perm:[1,0,3,2] row_mask:0xf bank_mask:0xf
	v_add_f32_dpp v55, v55, v55 quad_perm:[1,0,3,2] row_mask:0xf bank_mask:0xf
	v_add_f32_dpp v56, v56, v56 quad_perm:[1,0,3,2] row_mask:0xf bank_mask:0xf
	v_add_f32_dpp v57, v57, v57 quad_perm:[1,0,3,2] row_mask:0xf bank_mask:0xf
	v_add_f32_dpp v58, v58, v58 quad_perm:[1,0,3,2] row_mask:0xf bank_mask:0xf
	v_add_f32_dpp v59, v59, v59 quad_perm:[1,0,3,2] row_mask:0xf bank_mask:0xf
	v_add_f32_dpp v52, v52, v52 quad_perm:[2,3,0,1] row_mask:0xf bank_mask:0xf
	v_add_f32_dpp v53, v53, v53 quad_perm:[2,3,0,1] row_mask:0xf bank_mask:0xf
	v_add_f32_dpp v54, v54, v54 quad_perm:[2,3,0,1] row_mask:0xf bank_mask:0xf
	v_add_f32_dpp v55, v55, v55 quad_perm:[2,3,0,1] row_mask:0xf bank_mask:0xf
	v_add_f32_dpp v56, v56, v56 quad_perm:[2,3,0,1] row_mask:0xf bank_mask:0xf
	v_add_f32_dpp v57, v57, v57 quad_perm:[2,3,0,1] row_mask:0xf bank_mask:0xf
	v_add_f32_dpp v58, v58, v58 quad_perm:[2,3,0,1] row_mask:0xf bank_mask:0xf
	v_add_f32_dpp v59, v59, v59 quad_perm:[2,3,0,1] row_mask:0xf bank_mask:0xf
	v_add_f32_dpp v52, v52, v52 row_half_mirror row_mask:0xf bank_mask:0xf
	v_add_f32_dpp v53, v53, v53 row_half_mirror row_mask:0xf bank_mask:0xf
	v_add_f32_dpp v54, v54, v54 row_half_mirror row_mask:0xf bank_mask:0xf
	v_add_f32_dpp v55, v55, v55 row_half_mirror row_mask:0xf bank_mask:0xf
	v_add_f32_dpp v56, v56, v56 row_half_mirror row_mask:0xf bank_mask:0xf
	v_add_f32_dpp v57, v57, v57 row_half_mirror row_mask:0xf bank_mask:0xf
	v_add_f32_dpp v58, v58, v58 row_half_mirror row_mask:0xf bank_mask:0xf
	v_add_f32_dpp v59, v59, v59 row_half_mirror row_mask:0xf bank_mask:0xf
	v_mov_b32_e32 v60, 0x358637bd
	v_fmamk_f32 v52, v52, 0x3b800000, v60
	v_fmamk_f32 v53, v53, 0x3b800000, v60
	v_fmamk_f32 v54, v54, 0x3b800000, v60
	v_fmamk_f32 v55, v55, 0x3b800000, v60
	v_fmamk_f32 v56, v56, 0x3b800000, v60
	v_fmamk_f32 v57, v57, 0x3b800000, v60
	v_fmamk_f32 v58, v58, 0x3b800000, v60
	v_fmamk_f32 v59, v59, 0x3b800000, v60
	v_rsq_f32_e32 v52, v52
	v_rsq_f32_e32 v53, v53
	v_rsq_f32_e32 v54, v54
	v_rsq_f32_e32 v55, v55
	v_rsq_f32_e32 v56, v56
	v_rsq_f32_e32 v57, v57
	v_rsq_f32_e32 v58, v58
	v_rsq_f32_e32 v59, v59
	s_nop 0
	v_lshlrev_b32_e32 v62, 16, v20
	v_and_b32_e32 v63, 0xffff0000, v20
	v_mul_f32_e32 v62, v52, v62
	v_mul_f32_e32 v63, v52, v63
	v_cvt_pk_bf16_f32 v20, v62, v63
	v_lshlrev_b32_e32 v62, 16, v21
	v_and_b32_e32 v63, 0xffff0000, v21
	v_mul_f32_e32 v62, v52, v62
	v_mul_f32_e32 v63, v52, v63
	v_cvt_pk_bf16_f32 v21, v62, v63
	v_lshlrev_b32_e32 v62, 16, v22
	v_and_b32_e32 v63, 0xffff0000, v22
	v_mul_f32_e32 v62, v52, v62
	v_mul_f32_e32 v63, v52, v63
	v_cvt_pk_bf16_f32 v22, v62, v63
	v_lshlrev_b32_e32 v62, 16, v23
	v_and_b32_e32 v63, 0xffff0000, v23
	v_mul_f32_e32 v62, v52, v62
	v_mul_f32_e32 v63, v52, v63
	v_cvt_pk_bf16_f32 v23, v62, v63
	v_mov_b32_e32 v62, v64
	global_store_dwordx4 v62, v[20:23], s[96:97]
	v_lshlrev_b32_e32 v62, 16, v24
	v_and_b32_e32 v63, 0xffff0000, v24
	v_mul_f32_e32 v62, v53, v62
	v_mul_f32_e32 v63, v53, v63
	v_cvt_pk_bf16_f32 v24, v62, v63
	v_lshlrev_b32_e32 v62, 16, v25
	v_and_b32_e32 v63, 0xffff0000, v25
	v_mul_f32_e32 v62, v53, v62
	v_mul_f32_e32 v63, v53, v63
	v_cvt_pk_bf16_f32 v25, v62, v63
	v_lshlrev_b32_e32 v62, 16, v26
	v_and_b32_e32 v63, 0xffff0000, v26
	v_mul_f32_e32 v62, v53, v62
	v_mul_f32_e32 v63, v53, v63
	v_cvt_pk_bf16_f32 v26, v62, v63
	v_lshlrev_b32_e32 v62, 16, v27
	v_and_b32_e32 v63, 0xffff0000, v27
	v_mul_f32_e32 v62, v53, v62
	v_mul_f32_e32 v63, v53, v63
	v_cvt_pk_bf16_f32 v27, v62, v63
	v_add_u32_e32 v62, 0x2000, v64
	global_store_dwordx4 v62, v[24:27], s[96:97]
	v_lshlrev_b32_e32 v62, 16, v28
	v_and_b32_e32 v63, 0xffff0000, v28
	v_mul_f32_e32 v62, v54, v62
; __device__ __forceinline__ void st_wt16(void* p, u32x4 v) { asm volatile("global_store_dwordx4 %0, %1, off sc1\n\ts_nop 1" : : "v"(p), "v"(v) : "memory"); }
; __device__ __forceinline__ void p5_fixup(const Params& p) {
;     ...
;     for (int v0 = gtid; v0 < T_TOK * 128; v0 += 4 * gsz) {
;         u32x4 hv[4]; float4 s0[4], s1[4];
; #pragma unroll
;         for (int u = 0; u < 4; ++u) { const int v = v0 + u * gsz; if (v < T_TOK * 128) { const int row = v >> 7, head = (v >> 5) & 3;
;             hv[u] = __builtin_nontemporal_load((const u32x4*)(HM + (size_t)v * 8)); s0[u] = *(const float4*)(SSQ + ((size_t)row * 4 + head) * 8); s1[u] = *(const float4*)(SSQ + ((size_t)row * 4 + head) * 8 + 4); } }
; #pragma unroll
;         for (int u = 0; u < 4; ++u) { const int v = v0 + u * gsz; if (v < T_TOK * 128) {
;             const float ss = (s0[u].x + s0[u].y) + (s0[u].z + s0[u].w) + (s1[u].x + s1[u].y) + (s1[u].z + s1[u].w);
;             const float rstd = rsqrtf(ss * (1.0f / 256.0f) + EPS);
;             float f[8]; unpack8(hv[u], f);
; #pragma unroll
;             for (int e = 0; e < 8; ++e) f[e] *= rstd;
;             st_wt16(HM + (size_t)v * 8, pack8(f)); } }
;     }
	v_mul_f32_e32 v63, v54, v63
	v_cvt_pk_bf16_f32 v28, v62, v63
	v_lshlrev_b32_e32 v62, 16, v29
	v_and_b32_e32 v63, 0xffff0000, v29
	v_mul_f32_e32 v62, v54, v62
	v_mul_f32_e32 v63, v54, v63
	v_cvt_pk_bf16_f32 v29, v62, v63
	v_lshlrev_b32_e32 v62, 16, v30
	v_and_b32_e32 v63, 0xffff0000, v30
	v_mul_f32_e32 v62, v54, v62
	v_mul_f32_e32 v63, v54, v63
	v_cvt_pk_bf16_f32 v30, v62, v63
	v_lshlrev_b32_e32 v62, 16, v31
	v_and_b32_e32 v63, 0xffff0000, v31
	v_mul_f32_e32 v62, v54, v62
	v_mul_f32_e32 v63, v54, v63
	v_cvt_pk_bf16_f32 v31, v62, v63
	v_add_u32_e32 v62, 0x4000, v64
	global_store_dwordx4 v62, v[28:31], s[96:97]
	v_lshlrev_b32_e32 v62, 16, v32
	v_and_b32_e32 v63, 0xffff0000, v32
	v_mul_f32_e32 v62, v55, v62
	v_mul_f32_e32 v63, v55, v63
	v_cvt_pk_bf16_f32 v32, v62, v63
	v_lshlrev_b32_e32 v62, 16, v33
	v_and_b32_e32 v63, 0xffff0000, v33
	v_mul_f32_e32 v62, v55, v62
	v_mul_f32_e32 v63, v55, v63
	v_cvt_pk_bf16_f32 v33, v62, v63
	v_lshlrev_b32_e32 v62, 16, v34
	v_and_b32_e32 v63, 0xffff0000, v34
	v_mul_f32_e32 v62, v55, v62
	v_mul_f32_e32 v63, v55, v63
	v_cvt_pk_bf16_f32 v34, v62, v63
	v_lshlrev_b32_e32 v62, 16, v35
	v_and_b32_e32 v63, 0xffff0000, v35
	v_mul_f32_e32 v62, v55, v62
	v_mul_f32_e32 v63, v55, v63
	v_cvt_pk_bf16_f32 v35, v62, v63
	v_add_u32_e32 v62, 0x6000, v64
	global_store_dwordx4 v62, v[32:35], s[96:97]
	v_lshlrev_b32_e32 v62, 16, v36
	v_and_b32_e32 v63, 0xffff0000, v36
	v_mul_f32_e32 v62, v56, v62
	v_mul_f32_e32 v63, v56, v63
	v_cvt_pk_bf16_f32 v36, v62, v63
	v_lshlrev_b32_e32 v62, 16, v37
	v_and_b32_e32 v63, 0xffff0000, v37
	v_mul_f32_e32 v62, v56, v62
	v_mul_f32_e32 v63, v56, v63
	v_cvt_pk_bf16_f32 v37, v62, v63
	v_lshlrev_b32_e32 v62, 16, v38
	v_and_b32_e32 v63, 0xffff0000, v38
	v_mul_f32_e32 v62, v56, v62
	v_mul_f32_e32 v63, v56, v63
	v_cvt_pk_bf16_f32 v38, v62, v63
	v_lshlrev_b32_e32 v62, 16, v39
	v_and_b32_e32 v63, 0xffff0000, v39
	v_mul_f32_e32 v62, v56, v62
	v_mul_f32_e32 v63, v56, v63
	v_cvt_pk_bf16_f32 v39, v62, v63
	v_add_u32_e32 v62, 0x800000, v64
	global_store_dwordx4 v62, v[36:39], s[96:97]
	v_lshlrev_b32_e32 v62, 16, v40
	v_and_b32_e32 v63, 0xffff0000, v40
	v_mul_f32_e32 v62, v57, v62
	v_mul_f32_e32 v63, v57, v63
	v_cvt_pk_bf16_f32 v40, v62, v63
	v_lshlrev_b32_e32 v62, 16, v41
	v_and_b32_e32 v63, 0xffff0000, v41
	v_mul_f32_e32 v62, v57, v62
	v_mul_f32_e32 v63, v57, v63
	v_cvt_pk_bf16_f32 v41, v62, v63
	v_lshlrev_b32_e32 v62, 16, v42
	v_and_b32_e32 v63, 0xffff0000, v42
	v_mul_f32_e32 v62, v57, v62
	v_mul_f32_e32 v63, v57, v63
	v_cvt_pk_bf16_f32 v42, v62, v63
	v_lshlrev_b32_e32 v62, 16, v43
	v_and_b32_e32 v63, 0xffff0000, v43
	v_mul_f32_e32 v62, v57, v62
	v_mul_f32_e32 v63, v57, v63
	v_cvt_pk_bf16_f32 v43, v62, v63
	v_add_u32_e32 v62, 0x802000, v64
	global_store_dwordx4 v62, v[40:43], s[96:97]
	v_lshlrev_b32_e32 v62, 16, v44
	v_and_b32_e32 v63, 0xffff0000, v44
	v_mul_f32_e32 v62, v58, v62
	v_mul_f32_e32 v63, v58, v63
	v_cvt_pk_bf16_f32 v44, v62, v63
	v_lshlrev_b32_e32 v62, 16, v45
	v_and_b32_e32 v63, 0xffff0000, v45
	v_mul_f32_e32 v62, v58, v62
	v_mul_f32_e32 v63, v58, v63
	v_cvt_pk_bf16_f32 v45, v62, v63
	v_lshlrev_b32_e32 v62, 16, v46
	v_and_b32_e32 v63, 0xffff0000, v46
	v_mul_f32_e32 v62, v58, v62
	v_mul_f32_e32 v63, v58, v63
	v_cvt_pk_bf16_f32 v46, v62, v63
	v_lshlrev_b32_e32 v62, 16, v47
	v_and_b32_e32 v63, 0xffff0000, v47
	v_mul_f32_e32 v62, v58, v62
	v_mul_f32_e32 v63, v58, v63
	v_cvt_pk_bf16_f32 v47, v62, v63
	v_add_u32_e32 v62, 0x804000, v64
	global_store_dwordx4 v62, v[44:47], s[96:97]
	v_lshlrev_b32_e32 v62, 16, v48
	v_and_b32_e32 v63, 0xffff0000, v48
	v_mul_f32_e32 v62, v59, v62
	v_mul_f32_e32 v63, v59, v63
	v_cvt_pk_bf16_f32 v48, v62, v63
	v_lshlrev_b32_e32 v62, 16, v49
	v_and_b32_e32 v63, 0xffff0000, v49
	v_mul_f32_e32 v62, v59, v62
	v_mul_f32_e32 v63, v59, v63
	v_cvt_pk_bf16_f32 v49, v62, v63
	v_lshlrev_b32_e32 v62, 16, v50
	v_and_b32_e32 v63, 0xffff0000, v50
	v_mul_f32_e32 v62, v59, v62
	v_mul_f32_e32 v63, v59, v63
	v_cvt_pk_bf16_f32 v50, v62, v63
	v_lshlrev_b32_e32 v62, 16, v51
	v_and_b32_e32 v63, 0xffff0000, v51
	v_mul_f32_e32 v62, v59, v62
	v_mul_f32_e32 v63, v59, v63
	v_cvt_pk_bf16_f32 v51, v62, v63
	v_add_u32_e32 v62, 0x806000, v64
	global_store_dwordx4 v62, v[48:51], s[96:97]
	s_nop 1
	v_add_u32_e32 v62, 0x1000000, v64
	global_load_dwordx4 v[20:23], v62, s[96:97] nt
	v_add_u32_e32 v62, 0x1002000, v64
	global_load_dwordx4 v[24:27], v62, s[96:97] nt
	v_add_u32_e32 v62, 0x1004000, v64
	global_load_dwordx4 v[28:31], v62, s[96:97] nt
	v_add_u32_e32 v62, 0x1006000, v64
	global_load_dwordx4 v[32:35], v62, s[96:97] nt
	v_add_u32_e32 v62, 0x1800000, v64
	global_load_dwordx4 v[36:39], v62, s[96:97] nt
	v_add_u32_e32 v62, 0x1802000, v64
	global_load_dwordx4 v[40:43], v62, s[96:97] nt
	v_add_u32_e32 v62, 0x1804000, v64
	global_load_dwordx4 v[44:47], v62, s[96:97] nt
	v_add_u32_e32 v62, 0x1806000, v64
	global_load_dwordx4 v[48:51], v62, s[96:97] nt
	v_add_u32_e32 v62, 0x100000, v65
	global_load_dword v52, v62, s[88:89]
	v_add_u32_e32 v62, 0x100200, v65
	global_load_dword v53, v62, s[88:89]
	v_add_u32_e32 v62, 0x100400, v65
	global_load_dword v54, v62, s[88:89]
	v_add_u32_e32 v62, 0x100600, v65
	global_load_dword v55, v62, s[88:89]
	v_add_u32_e32 v62, 0x180000, v65
	global_load_dword v56, v62, s[88:89]
	v_add_u32_e32 v62, 0x180200, v65
	global_load_dword v57, v62, s[88:89]
	v_add_u32_e32 v62, 0x180400, v65
	global_load_dword v58, v62, s[88:89]
	v_add_u32_e32 v62, 0x180600, v65
	global_load_dword v59, v62, s[88:89]
	s_waitcnt vmcnt(0)
; __device__ __forceinline__ void st_wt16(void* p, u32x4 v) { asm volatile("global_store_dwordx4 %0, %1, off sc1\n\ts_nop 1" : : "v"(p), "v"(v) : "memory"); }
; __device__ __forceinline__ void p5_fixup(const Params& p) {
;     ...
;     for (int v0 = gtid; v0 < T_TOK * 128; v0 += 4 * gsz) {
;         u32x4 hv[4]; float4 s0[4], s1[4];
; #pragma unroll
;         for (int u = 0; u < 4; ++u) { const int v = v0 + u * gsz; if (v < T_TOK * 128) { const int row = v >> 7, head = (v >> 5) & 3;
;             hv[u] = __builtin_nontemporal_load((const u32x4*)(HM + (size_t)v * 8)); s0[u] = *(const float4*)(SSQ + ((size_t)row * 4 + head) * 8); s1[u] = *(const float4*)(SSQ + ((size_t)row * 4 + head) * 8 + 4); } }
; #pragma unroll
;         for (int u = 0; u < 4; ++u) { const int v = v0 + u * gsz; if (v < T_TOK * 128) {
;             const float ss = (s0[u].x + s0[u].y) + (s0[u].z + s0[u].w) + (s1[u].x + s1[u].y) + (s1[u].z + s1[u].w);
;             const float rstd = rsqrtf(ss * (1.0f / 256.0f) + EPS);
;             float f[8]; unpack8(hv[u], f);
; #pragma unroll
;             for (int e = 0; e < 8; ++e) f[e] *= rstd;
;             st_wt16(HM + (size_t)v * 8, pack8(f)); } }
;     }
	v_add_f32_dpp v52, v52, v52 quad_perm:[1,0,3,2] row_mask:0xf bank_mask:0xf
	v_add_f32_dpp v53, v53, v53 quad_perm:[1,0,3,2] row_mask:0xf bank_mask:0xf
	v_add_f32_dpp v54, v54, v54 quad_perm:[1,0,3,2] row_mask:0xf bank_mask:0xf
	v_add_f32_dpp v55, v55, v55 quad_perm:[1,0,3,2] row_mask:0xf bank_mask:0xf
	v_add_f32_dpp v56, v56, v56 quad_perm:[1,0,3,2] row_mask:0xf bank_mask:0xf
	v_add_f32_dpp v57, v57, v57 quad_perm:[1,0,3,2] row_mask:0xf bank_mask:0xf
	v_add_f32_dpp v58, v58, v58 quad_perm:[1,0,3,2] row_mask:0xf bank_mask:0xf
	v_add_f32_dpp v59, v59, v59 quad_perm:[1,0,3,2] row_mask:0xf bank_mask:0xf
	v_add_f32_dpp v52, v52, v52 quad_perm:[2,3,0,1] row_mask:0xf bank_mask:0xf
	v_add_f32_dpp v53, v53, v53 quad_perm:[2,3,0,1] row_mask:0xf bank_mask:0xf
	v_add_f32_dpp v54, v54, v54 quad_perm:[2,3,0,1] row_mask:0xf bank_mask:0xf
	v_add_f32_dpp v55, v55, v55 quad_perm:[2,3,0,1] row_mask:0xf bank_mask:0xf
	v_add_f32_dpp v56, v56, v56 quad_perm:[2,3,0,1] row_mask:0xf bank_mask:0xf
	v_add_f32_dpp v57, v57, v57 quad_perm:[2,3,0,1] row_mask:0xf bank_mask:0xf
	v_add_f32_dpp v58, v58, v58 quad_perm:[2,3,0,1] row_mask:0xf bank_mask:0xf
	v_add_f32_dpp v59, v59, v59 quad_perm:[2,3,0,1] row_mask:0xf bank_mask:0xf
	v_add_f32_dpp v52, v52, v52 row_half_mirror row_mask:0xf bank_mask:0xf
	v_add_f32_dpp v53, v53, v53 row_half_mirror row_mask:0xf bank_mask:0xf
	v_add_f32_dpp v54, v54, v54 row_half_mirror row_mask:0xf bank_mask:0xf
	v_add_f32_dpp v55, v55, v55 row_half_mirror row_mask:0xf bank_mask:0xf
	v_add_f32_dpp v56, v56, v56 row_half_mirror row_mask:0xf bank_mask:0xf
	v_add_f32_dpp v57, v57, v57 row_half_mirror row_mask:0xf bank_mask:0xf
	v_add_f32_dpp v58, v58, v58 row_half_mirror row_mask:0xf bank_mask:0xf
	v_add_f32_dpp v59, v59, v59 row_half_mirror row_mask:0xf bank_mask:0xf
	v_mov_b32_e32 v60, 0x358637bd
	v_fmamk_f32 v52, v52, 0x3b800000, v60
	v_fmamk_f32 v53, v53, 0x3b800000, v60
	v_fmamk_f32 v54, v54, 0x3b800000, v60
	v_fmamk_f32 v55, v55, 0x3b800000, v60
	v_fmamk_f32 v56, v56, 0x3b800000, v60
	v_fmamk_f32 v57, v57, 0x3b800000, v60
	v_fmamk_f32 v58, v58, 0x3b800000, v60
	v_fmamk_f32 v59, v59, 0x3b800000, v60
	v_rsq_f32_e32 v52, v52
	v_rsq_f32_e32 v53, v53
	v_rsq_f32_e32 v54, v54
	v_rsq_f32_e32 v55, v55
	v_rsq_f32_e32 v56, v56
	v_rsq_f32_e32 v57, v57
	v_rsq_f32_e32 v58, v58
	v_rsq_f32_e32 v59, v59
	s_nop 0
	v_lshlrev_b32_e32 v62, 16, v20
	v_and_b32_e32 v63, 0xffff0000, v20
	v_mul_f32_e32 v62, v52, v62
	v_mul_f32_e32 v63, v52, v63
	v_cvt_pk_bf16_f32 v20, v62, v63
	v_lshlrev_b32_e32 v62, 16, v21
	v_and_b32_e32 v63, 0xffff0000, v21
	v_mul_f32_e32 v62, v52, v62
	v_mul_f32_e32 v63, v52, v63
	v_cvt_pk_bf16_f32 v21, v62, v63
	v_lshlrev_b32_e32 v62, 16, v22
	v_and_b32_e32 v63, 0xffff0000, v22
	v_mul_f32_e32 v62, v52, v62
	v_mul_f32_e32 v63, v52, v63
	v_cvt_pk_bf16_f32 v22, v62, v63
	v_lshlrev_b32_e32 v62, 16, v23
	v_and_b32_e32 v63, 0xffff0000, v23
	v_mul_f32_e32 v62, v52, v62
	v_mul_f32_e32 v63, v52, v63
	v_cvt_pk_bf16_f32 v23, v62, v63
	v_add_u32_e32 v62, 0x1000000, v64
	global_store_dwordx4 v62, v[20:23], s[96:97]
	v_lshlrev_b32_e32 v62, 16, v24
	v_and_b32_e32 v63, 0xffff0000, v24
	v_mul_f32_e32 v62, v53, v62
	v_mul_f32_e32 v63, v53, v63
	v_cvt_pk_bf16_f32 v24, v62, v63
	v_lshlrev_b32_e32 v62, 16, v25
	v_and_b32_e32 v63, 0xffff0000, v25
	v_mul_f32_e32 v62, v53, v62
	v_mul_f32_e32 v63, v53, v63
	v_cvt_pk_bf16_f32 v25, v62, v63
	v_lshlrev_b32_e32 v62, 16, v26
	v_and_b32_e32 v63, 0xffff0000, v26
	v_mul_f32_e32 v62, v53, v62
	v_mul_f32_e32 v63, v53, v63
	v_cvt_pk_bf16_f32 v26, v62, v63
	v_lshlrev_b32_e32 v62, 16, v27
	v_and_b32_e32 v63, 0xffff0000, v27
	v_mul_f32_e32 v62, v53, v62
	v_mul_f32_e32 v63, v53, v63
	v_cvt_pk_bf16_f32 v27, v62, v63
	v_add_u32_e32 v62, 0x1002000, v64
	global_store_dwordx4 v62, v[24:27], s[96:97]
	v_lshlrev_b32_e32 v62, 16, v28
	v_and_b32_e32 v63, 0xffff0000, v28
	v_mul_f32_e32 v62, v54, v62
	v_mul_f32_e32 v63, v54, v63
	v_cvt_pk_bf16_f32 v28, v62, v63
	v_lshlrev_b32_e32 v62, 16, v29
	v_and_b32_e32 v63, 0xffff0000, v29
	v_mul_f32_e32 v62, v54, v62
	v_mul_f32_e32 v63, v54, v63
	v_cvt_pk_bf16_f32 v29, v62, v63
	v_lshlrev_b32_e32 v62, 16, v30
	v_and_b32_e32 v63, 0xffff0000, v30
	v_mul_f32_e32 v62, v54, v62
	v_mul_f32_e32 v63, v54, v63
	v_cvt_pk_bf16_f32 v30, v62, v63
	v_lshlrev_b32_e32 v62, 16, v31
	v_and_b32_e32 v63, 0xffff0000, v31
	v_mul_f32_e32 v62, v54, v62
	v_mul_f32_e32 v63, v54, v63
; __device__ __forceinline__ void st_wt16(void* p, u32x4 v) { asm volatile("global_store_dwordx4 %0, %1, off sc1\n\ts_nop 1" : : "v"(p), "v"(v) : "memory"); }
; __device__ __forceinline__ unsigned xb_ld(unsigned* p)              { return __hip_atomic_load(p, __ATOMIC_RELAXED, __HIP_MEMORY_SCOPE_AGENT); }
; #define XB_SPIN(cond, bar) do { unsigned _sp = 0; while (cond) { __builtin_amdgcn_s_sleep(1); \
;     if ((++_sp & 255u) == 0u) { if (xb_ld(&(bar)[XB_TMO])) break; if (_sp > XB_SPIN_CAP) { atomicAdd(&(bar)[XB_TMO], 1u); break; } } } } while (0)
; __device__ __forceinline__ void xcd_barrier(const XcdBarrier& b) {
;     ...
;             XB_SPIN(xb_ld(&bar[XB_XGEN(b.x)]) == gen, bar);
;             __builtin_amdgcn_fence(__ATOMIC_ACQUIRE, "agent");
; __device__ __forceinline__ void p5_fixup(const Params& p) {
;     ...
;         for (int u = 0; u < 4; ++u) { const int v = v0 + u * gsz; if (v < T_TOK * 128) { const int row = v >> 7, head = (v >> 5) & 3;
;             hv[u] = __builtin_nontemporal_load((const u32x4*)(HM + (size_t)v * 8)); s0[u] = *(const float4*)(SSQ + ((size_t)row * 4 + head) * 8); s1[u] = *(const float4*)(SSQ + ((size_t)row * 4 + head) * 8 + 4); } }
; #pragma unroll
;         for (int u = 0; u < 4; ++u) { const int v = v0 + u * gsz; if (v < T_TOK * 128) {
;             const float ss = (s0[u].x + s0[u].y) + (s0[u].z + s0[u].w) + (s1[u].x + s1[u].y) + (s1[u].z + s1[u].w);
;             const float rstd = rsqrtf(ss * (1.0f / 256.0f) + EPS);
;             float f[8]; unpack8(hv[u], f);
; #pragma unroll
;             for (int e = 0; e < 8; ++e) f[e] *= rstd;
;             st_wt16(HM + (size_t)v * 8, pack8(f)); } }
	v_cvt_pk_bf16_f32 v31, v62, v63
	v_add_u32_e32 v62, 0x1004000, v64
	global_store_dwordx4 v62, v[28:31], s[96:97]
	v_lshlrev_b32_e32 v62, 16, v32
	v_and_b32_e32 v63, 0xffff0000, v32
	v_mul_f32_e32 v62, v55, v62
	v_mul_f32_e32 v63, v55, v63
	v_cvt_pk_bf16_f32 v32, v62, v63
	v_lshlrev_b32_e32 v62, 16, v33
	v_and_b32_e32 v63, 0xffff0000, v33
	v_mul_f32_e32 v62, v55, v62
	v_mul_f32_e32 v63, v55, v63
	v_cvt_pk_bf16_f32 v33, v62, v63
	v_lshlrev_b32_e32 v62, 16, v34
	v_and_b32_e32 v63, 0xffff0000, v34
	v_mul_f32_e32 v62, v55, v62
	v_mul_f32_e32 v63, v55, v63
	v_cvt_pk_bf16_f32 v34, v62, v63
	v_lshlrev_b32_e32 v62, 16, v35
	v_and_b32_e32 v63, 0xffff0000, v35
	v_mul_f32_e32 v62, v55, v62
	v_mul_f32_e32 v63, v55, v63
	v_cvt_pk_bf16_f32 v35, v62, v63
	v_add_u32_e32 v62, 0x1006000, v64
	global_store_dwordx4 v62, v[32:35], s[96:97]
	v_lshlrev_b32_e32 v62, 16, v36
	v_and_b32_e32 v63, 0xffff0000, v36
	v_mul_f32_e32 v62, v56, v62
	v_mul_f32_e32 v63, v56, v63
	v_cvt_pk_bf16_f32 v36, v62, v63
	v_lshlrev_b32_e32 v62, 16, v37
	v_and_b32_e32 v63, 0xffff0000, v37
	v_mul_f32_e32 v62, v56, v62
	v_mul_f32_e32 v63, v56, v63
	v_cvt_pk_bf16_f32 v37, v62, v63
	v_lshlrev_b32_e32 v62, 16, v38
	v_and_b32_e32 v63, 0xffff0000, v38
	v_mul_f32_e32 v62, v56, v62
	v_mul_f32_e32 v63, v56, v63
	v_cvt_pk_bf16_f32 v38, v62, v63
	v_lshlrev_b32_e32 v62, 16, v39
	v_and_b32_e32 v63, 0xffff0000, v39
	v_mul_f32_e32 v62, v56, v62
	v_mul_f32_e32 v63, v56, v63
	v_cvt_pk_bf16_f32 v39, v62, v63
	v_add_u32_e32 v62, 0x1800000, v64
	global_store_dwordx4 v62, v[36:39], s[96:97]
	v_lshlrev_b32_e32 v62, 16, v40
	v_and_b32_e32 v63, 0xffff0000, v40
	v_mul_f32_e32 v62, v57, v62
	v_mul_f32_e32 v63, v57, v63
	v_cvt_pk_bf16_f32 v40, v62, v63
	v_lshlrev_b32_e32 v62, 16, v41
	v_and_b32_e32 v63, 0xffff0000, v41
	v_mul_f32_e32 v62, v57, v62
	v_mul_f32_e32 v63, v57, v63
	v_cvt_pk_bf16_f32 v41, v62, v63
	v_lshlrev_b32_e32 v62, 16, v42
	v_and_b32_e32 v63, 0xffff0000, v42
	v_mul_f32_e32 v62, v57, v62
	v_mul_f32_e32 v63, v57, v63
	v_cvt_pk_bf16_f32 v42, v62, v63
	v_lshlrev_b32_e32 v62, 16, v43
	v_and_b32_e32 v63, 0xffff0000, v43
	v_mul_f32_e32 v62, v57, v62
	v_mul_f32_e32 v63, v57, v63
	v_cvt_pk_bf16_f32 v43, v62, v63
	v_add_u32_e32 v62, 0x1802000, v64
	global_store_dwordx4 v62, v[40:43], s[96:97]
	v_lshlrev_b32_e32 v62, 16, v44
	v_and_b32_e32 v63, 0xffff0000, v44
	v_mul_f32_e32 v62, v58, v62
	v_mul_f32_e32 v63, v58, v63
	v_cvt_pk_bf16_f32 v44, v62, v63
	v_lshlrev_b32_e32 v62, 16, v45
	v_and_b32_e32 v63, 0xffff0000, v45
	v_mul_f32_e32 v62, v58, v62
	v_mul_f32_e32 v63, v58, v63
	v_cvt_pk_bf16_f32 v45, v62, v63
	v_lshlrev_b32_e32 v62, 16, v46
	v_and_b32_e32 v63, 0xffff0000, v46
	v_mul_f32_e32 v62, v58, v62
	v_mul_f32_e32 v63, v58, v63
	v_cvt_pk_bf16_f32 v46, v62, v63
	v_lshlrev_b32_e32 v62, 16, v47
	v_and_b32_e32 v63, 0xffff0000, v47
	v_mul_f32_e32 v62, v58, v62
	v_mul_f32_e32 v63, v58, v63
	v_cvt_pk_bf16_f32 v47, v62, v63
	v_add_u32_e32 v62, 0x1804000, v64
	global_store_dwordx4 v62, v[44:47], s[96:97]
	v_lshlrev_b32_e32 v62, 16, v48
	v_and_b32_e32 v63, 0xffff0000, v48
	v_mul_f32_e32 v62, v59, v62
	v_mul_f32_e32 v63, v59, v63
	v_cvt_pk_bf16_f32 v48, v62, v63
	v_lshlrev_b32_e32 v62, 16, v49
	v_and_b32_e32 v63, 0xffff0000, v49
	v_mul_f32_e32 v62, v59, v62
	v_mul_f32_e32 v63, v59, v63
	v_cvt_pk_bf16_f32 v49, v62, v63
	v_lshlrev_b32_e32 v62, 16, v50
	v_and_b32_e32 v63, 0xffff0000, v50
	v_mul_f32_e32 v62, v59, v62
	v_mul_f32_e32 v63, v59, v63
	v_cvt_pk_bf16_f32 v50, v62, v63
	v_lshlrev_b32_e32 v62, 16, v51
	v_and_b32_e32 v63, 0xffff0000, v51
	v_mul_f32_e32 v62, v59, v62
	v_mul_f32_e32 v63, v59, v63
	v_cvt_pk_bf16_f32 v51, v62, v63
	v_add_u32_e32 v62, 0x1806000, v64
	global_store_dwordx4 v62, v[48:51], s[96:97]
	s_nop 1
.Lf4_done:
	s_cmp_eq_u32 s101, 1
	s_cbranch_scc0 .Lw4_done
	s_mov_b32 s101, 0
	v_readfirstlane_b32 s96, v212
	s_nop 3
	s_cmp_lg_u32 s96, 0
	s_cbranch_scc1 .Lw4_bar
	v_readlane_b32 s96, v254, 3
	s_nop 3
	s_lshl_b32 s96, s96, 8
	v_mov_b32_e32 v250, 0xffc3500
	v_mov_b32_e32 v251, 0xffc2400
	v_add_u32_e32 v251, s96, v251
	s_mov_b32 s96, 0
.Lw4_spin:
	global_load_dword v252, v250, s[88:89] sc1
	global_load_dword v253, v251, s[88:89] sc1
	s_waitcnt vmcnt(0)
	v_min_u32_e32 v252, v252, v253
	s_nop 1
	v_readfirstlane_b32 s97, v252
	s_nop 3
	s_cmp_ge_u32 s97, 5
	s_cbranch_scc1 .Lw4_acq
	s_sleep 1
	s_add_i32 s96, s96, 1
	s_cmp_lt_u32 s96, 0x40000
	s_cbranch_scc1 .Lw4_spin

; #define LAS __attribute__((address_space(3)))
; __device__ __forceinline__ void p4_attn(const Params& p, LAS unsigned char* lds, const int dummy) {
;     const int tid = threadIdx.x, wid = __builtin_amdgcn_readfirstlane(tid >> 6), lane = tid & 63, r = lane & 15, q = lane >> 4;
;     unsigned char* ws = p.ws;
;     bf16_t* R1 = (bf16_t*)(ws + WS_R1);
;     const float* RC = (const float*)(ws + WS_ROPE); const float* RS = RC + 2048 * 16;
;     float* ML = (float*)((unsigned char*)p.out + OUT_ML);
;     LAS unsigned char* KA = lds + AT_KA; LAS unsigned char* VB = lds + AT_VB;
;     const float QSCALE = 0.08838834764831845f * 1.4426950408889634f;
;     u32x4 kr[8], vr[8];
;     int it = blockIdx.x;
;     if (it < 1536) { const AttnItem a0 = attn_item(it); attn_load(R1, a0, tid, kr, vr); }
.Lw4_done:
	s_mov_b64 s[96:97], -1
	v_readfirstlane_b32 s100, v212
	s_nop 3
	s_cmp_ge_u32 s100, 0x100
	s_cbranch_scc0 .Lprio5_done
	s_setprio 1
.Lprio5_done:
	s_movk_i32 s98, 0x64
	s_cmp_lg_u32 s82, 0x100
	s_cbranch_scc1 .Lhm_nofuse
	s_movk_i32 s98, 0x64
	s_mov_b32 s99, 1
	v_readlane_b32 s100, v254, 23
	v_readlane_b32 s101, v254, 24
	v_lshlrev_b32_e32 v250, 4, v212
	v_mov_b32_e32 v251, s84
	v_lshl_add_u32 v250, v251, 15, v250
	v_lshlrev_b32_e32 v251, 11, v251
	v_and_b32_e32 v252, 0x1e0, v212
	v_add_u32_e32 v251, v251, v252
	v_and_b32_e32 v252, 7, v212
	v_lshl_add_u32 v251, v252, 2, v251
	v_add_u32_e32 v251, 0xfd80000, v251
